# P13 epilogue: all 16 residual loads of a tile issued up front into dead fragment registers; per-chunk store->load->vmcnt(0) chain removed
# baseline (speedup 1.0000x reference)
.LBB0_1080:
	v_lshl_add_u32 v148, s51, 8, v150
	v_lshl_or_b32 v146, s52, 8, v152
	v_ashrrev_i32_e32 v149, 31, v148
	v_ashrrev_i32_e32 v147, 31, v146
	v_lshlrev_b64 v[144:145], 12, v[148:149]
	v_lshl_add_u64 v[144:145], v[144:145], 0, v[146:147]
	v_lshlrev_b64 v[144:145], 1, v[144:145]
	v_lshl_add_u64 v[160:161], s[74:75], 0, v[144:145]
	global_load_dwordx4 v[156:159], v[160:161], off
	global_load_dwordx4 v[168:171], v[160:161], off offset:256
	s_mov_b32 s100, 0x20000
	s_mov_b32 s101, 0
	v_lshl_add_u64 v[172:173], s[100:101], 0, v[160:161]
	global_load_dwordx4 v[172:175], v[172:173], off
	v_lshl_add_u64 v[176:177], s[100:101], 0, v[160:161]
	global_load_dwordx4 v[176:179], v[176:177], off offset:256
	s_mov_b32 s100, 0x40000
	s_mov_b32 s101, 0
	v_lshl_add_u64 v[180:181], s[100:101], 0, v[160:161]
	global_load_dwordx4 v[180:183], v[180:181], off
	v_lshl_add_u64 v[184:185], s[100:101], 0, v[160:161]
	global_load_dwordx4 v[184:187], v[184:185], off offset:256
	s_mov_b32 s100, 0x60000
	s_mov_b32 s101, 0
	v_lshl_add_u64 v[188:189], s[100:101], 0, v[160:161]
	global_load_dwordx4 v[188:191], v[188:189], off
	v_lshl_add_u64 v[192:193], s[100:101], 0, v[160:161]
	global_load_dwordx4 v[192:195], v[192:193], off offset:256
	v_lshl_add_u64 v[196:197], s[16:17], 0, v[160:161]
	global_load_dwordx4 v[196:199], v[196:197], off
	v_lshl_add_u64 v[200:201], s[16:17], 0, v[160:161]
	global_load_dwordx4 v[200:203], v[200:201], off offset:256
	v_lshl_add_u64 v[204:205], s[18:19], 0, v[160:161]
	global_load_dwordx4 v[204:207], v[204:205], off
	v_lshl_add_u64 v[208:209], s[18:19], 0, v[160:161]
	global_load_dwordx4 v[208:211], v[208:209], off offset:256
	v_lshl_add_u64 v[212:213], s[20:21], 0, v[160:161]
	global_load_dwordx4 v[212:215], v[212:213], off
	v_lshl_add_u64 v[226:227], s[20:21], 0, v[160:161]
	global_load_dwordx4 v[226:229], v[226:227], off offset:256
	v_lshl_add_u64 v[230:231], s[22:23], 0, v[160:161]
	global_load_dwordx4 v[230:233], v[230:231], off
	v_lshl_add_u64 v[234:235], s[22:23], 0, v[160:161]
	global_load_dwordx4 v[234:237], v[234:235], off offset:256
	v_lshl_add_u64 v[162:163], s[86:87], 0, v[144:145]
	s_and_b64 vcc, exec, s[0:1]
	s_mov_b64 s[0:1], -1
	s_waitcnt vmcnt(0)
	v_lshlrev_b32_e32 v164, 16, v156
	v_and_b32_e32 v165, 0xffff0000, v156
	v_lshlrev_b32_e32 v156, 16, v157
	v_and_b32_e32 v157, 0xffff0000, v157
	v_lshlrev_b32_e32 v166, 16, v158
	v_and_b32_e32 v167, 0xffff0000, v158
	v_lshlrev_b32_e32 v158, 16, v159
	v_and_b32_e32 v159, 0xffff0000, v159
	v_pk_add_f32 v[126:127], v[126:127], v[156:157]
	v_pk_add_f32 v[156:157], v[122:123], v[158:159]
	v_pk_add_f32 v[122:123], v[120:121], v[166:167]
	v_pk_add_f32 v[124:125], v[124:125], v[164:165]
	s_nop 0
	v_cvt_pk_bf16_f32 v120, v124, v125
	v_cvt_pk_bf16_f32 v121, v126, v127
	v_cvt_pk_bf16_f32 v122, v122, v123
	v_cvt_pk_bf16_f32 v123, v156, v157
	global_store_dwordx4 v[162:163], v[120:123], off
	s_nop 2
	v_mov_b64_e32 v[120:121], v[168:169]
	v_mov_b64_e32 v[122:123], v[170:171]
	v_or_b32_e32 v124, 16, v148
	v_ashrrev_i32_e32 v125, 31, v124
	v_lshlrev_b64 v[124:125], 12, v[124:125]
	v_lshl_add_u64 v[124:125], v[124:125], 0, v[146:147]
	v_lshlrev_b64 v[124:125], 1, v[124:125]
	v_lshl_add_u64 v[126:127], s[74:75], 0, v[124:125]
	v_lshlrev_b32_e32 v156, 16, v120
	v_and_b32_e32 v157, 0xffff0000, v120
	v_lshlrev_b32_e32 v120, 16, v121
	v_and_b32_e32 v121, 0xffff0000, v121
	v_lshlrev_b32_e32 v158, 16, v122
	v_and_b32_e32 v159, 0xffff0000, v122
	v_lshlrev_b32_e32 v122, 16, v123
	v_and_b32_e32 v123, 0xffff0000, v123
	v_pk_add_f32 v[118:119], v[118:119], v[120:121]
	v_pk_add_f32 v[120:121], v[114:115], v[122:123]
	v_pk_add_f32 v[114:115], v[112:113], v[158:159]
	v_pk_add_f32 v[116:117], v[116:117], v[156:157]
	s_nop 0
	v_cvt_pk_bf16_f32 v112, v116, v117
	v_cvt_pk_bf16_f32 v113, v118, v119
	v_cvt_pk_bf16_f32 v114, v114, v115
	v_cvt_pk_bf16_f32 v115, v120, v121
	global_store_dwordx4 v[162:163], v[112:115], off offset:256
	s_nop 2
	v_mov_b64_e32 v[112:113], v[172:173]
	v_mov_b64_e32 v[114:115], v[174:175]
	v_lshl_add_u64 v[116:117], s[86:87], 0, v[124:125]
	v_lshlrev_b32_e32 v118, 16, v112
	v_and_b32_e32 v119, 0xffff0000, v112
	v_lshlrev_b32_e32 v112, 16, v113
	v_and_b32_e32 v113, 0xffff0000, v113
	v_lshlrev_b32_e32 v120, 16, v114
	v_and_b32_e32 v121, 0xffff0000, v114
	v_lshlrev_b32_e32 v114, 16, v115
	v_and_b32_e32 v115, 0xffff0000, v115
	v_pk_add_f32 v[110:111], v[110:111], v[112:113]
	v_pk_add_f32 v[112:113], v[106:107], v[114:115]
	v_pk_add_f32 v[106:107], v[104:105], v[120:121]
	v_pk_add_f32 v[108:109], v[108:109], v[118:119]
	s_nop 0
	v_cvt_pk_bf16_f32 v104, v108, v109
	v_cvt_pk_bf16_f32 v105, v110, v111
	v_cvt_pk_bf16_f32 v106, v106, v107
	v_cvt_pk_bf16_f32 v107, v112, v113
	global_store_dwordx4 v[116:117], v[104:107], off
	s_nop 2
	v_mov_b64_e32 v[104:105], v[176:177]
	v_mov_b64_e32 v[106:107], v[178:179]
	v_or_b32_e32 v108, 32, v148
	v_ashrrev_i32_e32 v109, 31, v108
	v_lshlrev_b64 v[108:109], 12, v[108:109]
	v_lshl_add_u64 v[108:109], v[108:109], 0, v[146:147]
	v_lshlrev_b64 v[108:109], 1, v[108:109]
	v_lshl_add_u64 v[110:111], s[74:75], 0, v[108:109]
	v_lshlrev_b32_e32 v112, 16, v104
	v_and_b32_e32 v113, 0xffff0000, v104
	v_lshlrev_b32_e32 v104, 16, v105
	v_and_b32_e32 v105, 0xffff0000, v105
	v_lshlrev_b32_e32 v114, 16, v106
	v_and_b32_e32 v115, 0xffff0000, v106
	v_lshlrev_b32_e32 v106, 16, v107
	v_and_b32_e32 v107, 0xffff0000, v107
	v_pk_add_f32 v[102:103], v[102:103], v[104:105]
	v_pk_add_f32 v[104:105], v[98:99], v[106:107]
	v_pk_add_f32 v[98:99], v[96:97], v[114:115]
	v_pk_add_f32 v[100:101], v[100:101], v[112:113]
	s_nop 0
	v_cvt_pk_bf16_f32 v96, v100, v101
	v_cvt_pk_bf16_f32 v97, v102, v103
	v_cvt_pk_bf16_f32 v98, v98, v99
	v_cvt_pk_bf16_f32 v99, v104, v105
	global_store_dwordx4 v[116:117], v[96:99], off offset:256
	s_nop 2
	v_mov_b64_e32 v[96:97], v[180:181]
	v_mov_b64_e32 v[98:99], v[182:183]
	v_lshl_add_u64 v[100:101], s[86:87], 0, v[108:109]
	v_lshlrev_b32_e32 v102, 16, v96
	v_and_b32_e32 v103, 0xffff0000, v96
	v_lshlrev_b32_e32 v96, 16, v97
	v_and_b32_e32 v97, 0xffff0000, v97
	v_lshlrev_b32_e32 v104, 16, v98
	v_and_b32_e32 v105, 0xffff0000, v98
	v_lshlrev_b32_e32 v98, 16, v99
	v_and_b32_e32 v99, 0xffff0000, v99
	v_pk_add_f32 v[94:95], v[94:95], v[96:97]
	v_pk_add_f32 v[96:97], v[90:91], v[98:99]
	v_pk_add_f32 v[90:91], v[88:89], v[104:105]
	v_pk_add_f32 v[92:93], v[92:93], v[102:103]
	s_nop 0
	v_cvt_pk_bf16_f32 v88, v92, v93
	v_cvt_pk_bf16_f32 v89, v94, v95
	v_cvt_pk_bf16_f32 v90, v90, v91
	v_cvt_pk_bf16_f32 v91, v96, v97
	global_store_dwordx4 v[100:101], v[88:91], off
	s_nop 2
	v_mov_b64_e32 v[88:89], v[184:185]
	v_mov_b64_e32 v[90:91], v[186:187]
	v_or_b32_e32 v92, 48, v148
	v_ashrrev_i32_e32 v93, 31, v92
	v_lshlrev_b64 v[92:93], 12, v[92:93]
	v_lshl_add_u64 v[92:93], v[92:93], 0, v[146:147]
	v_lshlrev_b64 v[92:93], 1, v[92:93]
	v_lshl_add_u64 v[94:95], s[74:75], 0, v[92:93]
	v_lshlrev_b32_e32 v96, 16, v88
	v_and_b32_e32 v97, 0xffff0000, v88
	v_lshlrev_b32_e32 v88, 16, v89
	v_and_b32_e32 v89, 0xffff0000, v89
	v_lshlrev_b32_e32 v98, 16, v90
	v_and_b32_e32 v99, 0xffff0000, v90
	v_lshlrev_b32_e32 v90, 16, v91
	v_and_b32_e32 v91, 0xffff0000, v91
	v_pk_add_f32 v[86:87], v[86:87], v[88:89]
	v_pk_add_f32 v[88:89], v[82:83], v[90:91]
	v_pk_add_f32 v[82:83], v[80:81], v[98:99]
	v_pk_add_f32 v[84:85], v[84:85], v[96:97]
	s_nop 0
	v_cvt_pk_bf16_f32 v80, v84, v85
	v_cvt_pk_bf16_f32 v81, v86, v87
	v_cvt_pk_bf16_f32 v82, v82, v83
	v_cvt_pk_bf16_f32 v83, v88, v89
	global_store_dwordx4 v[100:101], v[80:83], off offset:256
	s_nop 2
	v_mov_b64_e32 v[80:81], v[188:189]
	v_mov_b64_e32 v[82:83], v[190:191]
	v_lshl_add_u64 v[84:85], s[86:87], 0, v[92:93]
	v_lshlrev_b32_e32 v86, 16, v80
	v_and_b32_e32 v87, 0xffff0000, v80
	v_lshlrev_b32_e32 v80, 16, v81
	v_and_b32_e32 v81, 0xffff0000, v81
	v_lshlrev_b32_e32 v88, 16, v82
	v_and_b32_e32 v89, 0xffff0000, v82
	v_lshlrev_b32_e32 v82, 16, v83
	v_and_b32_e32 v83, 0xffff0000, v83
	v_pk_add_f32 v[78:79], v[78:79], v[80:81]
	v_pk_add_f32 v[80:81], v[74:75], v[82:83]
	v_pk_add_f32 v[74:75], v[72:73], v[88:89]
	v_pk_add_f32 v[76:77], v[76:77], v[86:87]
	s_nop 0
	v_cvt_pk_bf16_f32 v72, v76, v77
	v_cvt_pk_bf16_f32 v73, v78, v79
	v_cvt_pk_bf16_f32 v74, v74, v75
	v_cvt_pk_bf16_f32 v75, v80, v81
	global_store_dwordx4 v[84:85], v[72:75], off
	s_nop 2
	v_mov_b64_e32 v[72:73], v[192:193]
	v_mov_b64_e32 v[74:75], v[194:195]
	v_lshl_add_u64 v[76:77], v[144:145], 0, s[16:17]
	v_lshl_add_u64 v[78:79], s[74:75], 0, v[76:77]
	v_lshlrev_b32_e32 v80, 16, v72
	v_and_b32_e32 v81, 0xffff0000, v72
	v_lshlrev_b32_e32 v72, 16, v73
	v_and_b32_e32 v73, 0xffff0000, v73
	v_lshlrev_b32_e32 v82, 16, v74
	v_and_b32_e32 v83, 0xffff0000, v74
	v_lshlrev_b32_e32 v74, 16, v75
	v_and_b32_e32 v75, 0xffff0000, v75
	v_pk_add_f32 v[70:71], v[70:71], v[72:73]
	v_pk_add_f32 v[72:73], v[66:67], v[74:75]
	v_pk_add_f32 v[66:67], v[64:65], v[82:83]
	v_pk_add_f32 v[68:69], v[68:69], v[80:81]
	s_nop 0
	v_cvt_pk_bf16_f32 v64, v68, v69
	v_cvt_pk_bf16_f32 v65, v70, v71
	v_cvt_pk_bf16_f32 v66, v66, v67
	v_cvt_pk_bf16_f32 v67, v72, v73
	global_store_dwordx4 v[84:85], v[64:67], off offset:256
	s_nop 2
	v_mov_b64_e32 v[64:65], v[196:197]
	v_mov_b64_e32 v[66:67], v[198:199]
	v_lshl_add_u64 v[68:69], s[86:87], 0, v[76:77]
	v_lshlrev_b32_e32 v70, 16, v64
	v_and_b32_e32 v71, 0xffff0000, v64
	v_lshlrev_b32_e32 v64, 16, v65
	v_and_b32_e32 v65, 0xffff0000, v65
	v_lshlrev_b32_e32 v72, 16, v66
	v_and_b32_e32 v73, 0xffff0000, v66
	v_lshlrev_b32_e32 v66, 16, v67
	v_and_b32_e32 v67, 0xffff0000, v67
	v_pk_add_f32 v[62:63], v[62:63], v[64:65]
	v_pk_add_f32 v[64:65], v[58:59], v[66:67]
	v_pk_add_f32 v[58:59], v[56:57], v[72:73]
	v_pk_add_f32 v[60:61], v[60:61], v[70:71]
	s_nop 0
	v_cvt_pk_bf16_f32 v56, v60, v61
	v_cvt_pk_bf16_f32 v57, v62, v63
	v_cvt_pk_bf16_f32 v58, v58, v59
	v_cvt_pk_bf16_f32 v59, v64, v65
	global_store_dwordx4 v[68:69], v[56:59], off
	s_nop 2
	v_mov_b64_e32 v[56:57], v[200:201]
	v_mov_b64_e32 v[58:59], v[202:203]
	v_lshl_add_u64 v[60:61], v[144:145], 0, s[18:19]
	v_lshl_add_u64 v[62:63], s[74:75], 0, v[60:61]
	v_lshlrev_b32_e32 v64, 16, v56
	v_and_b32_e32 v65, 0xffff0000, v56
	v_lshlrev_b32_e32 v56, 16, v57
	v_and_b32_e32 v57, 0xffff0000, v57
	v_lshlrev_b32_e32 v66, 16, v58
	v_and_b32_e32 v67, 0xffff0000, v58
	v_lshlrev_b32_e32 v58, 16, v59
	v_and_b32_e32 v59, 0xffff0000, v59
	v_pk_add_f32 v[54:55], v[54:55], v[56:57]
	v_pk_add_f32 v[56:57], v[50:51], v[58:59]
	v_pk_add_f32 v[50:51], v[48:49], v[66:67]
	v_pk_add_f32 v[52:53], v[52:53], v[64:65]
	s_nop 0
	v_cvt_pk_bf16_f32 v48, v52, v53
	v_cvt_pk_bf16_f32 v49, v54, v55
	v_cvt_pk_bf16_f32 v50, v50, v51
	v_cvt_pk_bf16_f32 v51, v56, v57
	global_store_dwordx4 v[68:69], v[48:51], off offset:256
	s_nop 2
	v_mov_b64_e32 v[48:49], v[204:205]
	v_mov_b64_e32 v[50:51], v[206:207]
	v_lshl_add_u64 v[52:53], s[86:87], 0, v[60:61]
	v_lshlrev_b32_e32 v54, 16, v48
	v_and_b32_e32 v55, 0xffff0000, v48
	v_lshlrev_b32_e32 v48, 16, v49
	v_and_b32_e32 v49, 0xffff0000, v49
	v_lshlrev_b32_e32 v56, 16, v50
	v_and_b32_e32 v57, 0xffff0000, v50
	v_lshlrev_b32_e32 v50, 16, v51
	v_and_b32_e32 v51, 0xffff0000, v51
	v_pk_add_f32 v[46:47], v[46:47], v[48:49]
	v_pk_add_f32 v[48:49], v[42:43], v[50:51]
	v_pk_add_f32 v[42:43], v[40:41], v[56:57]
	v_pk_add_f32 v[44:45], v[44:45], v[54:55]
	s_nop 0
	v_cvt_pk_bf16_f32 v40, v44, v45
	v_cvt_pk_bf16_f32 v41, v46, v47
	v_cvt_pk_bf16_f32 v42, v42, v43
	v_cvt_pk_bf16_f32 v43, v48, v49
	global_store_dwordx4 v[52:53], v[40:43], off
	s_nop 2
	v_mov_b64_e32 v[40:41], v[208:209]
	v_mov_b64_e32 v[42:43], v[210:211]
	v_lshl_add_u64 v[44:45], v[144:145], 0, s[20:21]
	v_lshl_add_u64 v[46:47], s[74:75], 0, v[44:45]
	v_lshlrev_b32_e32 v48, 16, v40
	v_and_b32_e32 v49, 0xffff0000, v40
	v_lshlrev_b32_e32 v40, 16, v41
	v_and_b32_e32 v41, 0xffff0000, v41
	v_lshlrev_b32_e32 v50, 16, v42
	v_and_b32_e32 v51, 0xffff0000, v42
	v_lshlrev_b32_e32 v42, 16, v43
	v_and_b32_e32 v43, 0xffff0000, v43
	v_pk_add_f32 v[38:39], v[38:39], v[40:41]
	v_pk_add_f32 v[40:41], v[34:35], v[42:43]
	v_pk_add_f32 v[34:35], v[32:33], v[50:51]
	v_pk_add_f32 v[36:37], v[36:37], v[48:49]
	s_nop 0
	v_cvt_pk_bf16_f32 v32, v36, v37
	v_cvt_pk_bf16_f32 v33, v38, v39
	v_cvt_pk_bf16_f32 v34, v34, v35
	v_cvt_pk_bf16_f32 v35, v40, v41
	global_store_dwordx4 v[52:53], v[32:35], off offset:256
	s_nop 2
	v_mov_b64_e32 v[32:33], v[212:213]
	v_mov_b64_e32 v[34:35], v[214:215]
	v_lshl_add_u64 v[36:37], s[86:87], 0, v[44:45]
	v_lshlrev_b32_e32 v38, 16, v32
	v_and_b32_e32 v39, 0xffff0000, v32
	v_lshlrev_b32_e32 v32, 16, v33
	v_and_b32_e32 v33, 0xffff0000, v33
	v_lshlrev_b32_e32 v40, 16, v34
	v_and_b32_e32 v41, 0xffff0000, v34
	v_lshlrev_b32_e32 v34, 16, v35
	v_and_b32_e32 v35, 0xffff0000, v35
	v_pk_add_f32 v[30:31], v[30:31], v[32:33]
	v_pk_add_f32 v[32:33], v[26:27], v[34:35]
	v_pk_add_f32 v[26:27], v[24:25], v[40:41]
	v_pk_add_f32 v[28:29], v[28:29], v[38:39]
	s_nop 0
	v_cvt_pk_bf16_f32 v24, v28, v29
	v_cvt_pk_bf16_f32 v25, v30, v31
	v_cvt_pk_bf16_f32 v26, v26, v27
	v_cvt_pk_bf16_f32 v27, v32, v33
	global_store_dwordx4 v[36:37], v[24:27], off
	s_nop 2
	v_mov_b64_e32 v[24:25], v[226:227]
	v_mov_b64_e32 v[26:27], v[228:229]
	v_lshl_add_u64 v[28:29], v[144:145], 0, s[22:23]
	v_lshl_add_u64 v[30:31], s[74:75], 0, v[28:29]
	v_lshlrev_b32_e32 v32, 16, v24
	v_and_b32_e32 v33, 0xffff0000, v24
	v_lshlrev_b32_e32 v24, 16, v25
	v_and_b32_e32 v25, 0xffff0000, v25
	v_lshlrev_b32_e32 v34, 16, v26
	v_and_b32_e32 v35, 0xffff0000, v26
	v_lshlrev_b32_e32 v26, 16, v27
	v_and_b32_e32 v27, 0xffff0000, v27
	v_pk_add_f32 v[22:23], v[22:23], v[24:25]
	v_pk_add_f32 v[24:25], v[18:19], v[26:27]
	v_pk_add_f32 v[18:19], v[16:17], v[34:35]
	v_pk_add_f32 v[20:21], v[20:21], v[32:33]
	s_nop 0
	v_cvt_pk_bf16_f32 v16, v20, v21
	v_cvt_pk_bf16_f32 v17, v22, v23
	v_cvt_pk_bf16_f32 v18, v18, v19
	v_cvt_pk_bf16_f32 v19, v24, v25
	global_store_dwordx4 v[36:37], v[16:19], off offset:256
	s_nop 2
	v_mov_b64_e32 v[16:17], v[230:231]
	v_mov_b64_e32 v[18:19], v[232:233]
	v_lshl_add_u64 v[20:21], s[86:87], 0, v[28:29]
	v_lshlrev_b32_e32 v22, 16, v16
	v_and_b32_e32 v23, 0xffff0000, v16
	v_lshlrev_b32_e32 v16, 16, v17
	v_and_b32_e32 v17, 0xffff0000, v17
	v_lshlrev_b32_e32 v24, 16, v18
	v_and_b32_e32 v25, 0xffff0000, v18
	v_lshlrev_b32_e32 v18, 16, v19
	v_and_b32_e32 v19, 0xffff0000, v19
	v_pk_add_f32 v[14:15], v[14:15], v[16:17]
	v_pk_add_f32 v[16:17], v[10:11], v[18:19]
	v_pk_add_f32 v[10:11], v[8:9], v[24:25]
	v_pk_add_f32 v[12:13], v[12:13], v[22:23]
	s_nop 0
	v_cvt_pk_bf16_f32 v8, v12, v13
	v_cvt_pk_bf16_f32 v9, v14, v15
	v_cvt_pk_bf16_f32 v10, v10, v11
	v_cvt_pk_bf16_f32 v11, v16, v17
	global_store_dwordx4 v[20:21], v[8:11], off
	s_nop 2
	v_mov_b64_e32 v[8:9], v[234:235]
	v_mov_b64_e32 v[10:11], v[236:237]
	v_lshlrev_b32_e32 v12, 16, v8
	v_and_b32_e32 v13, 0xffff0000, v8
	v_lshlrev_b32_e32 v8, 16, v9
	v_and_b32_e32 v9, 0xffff0000, v9
	v_lshlrev_b32_e32 v14, 16, v10
	v_and_b32_e32 v15, 0xffff0000, v10
	v_lshlrev_b32_e32 v10, 16, v11
	v_and_b32_e32 v11, 0xffff0000, v11
	v_pk_add_f32 v[6:7], v[6:7], v[8:9]
	v_pk_add_f32 v[8:9], v[2:3], v[10:11]
	v_pk_add_f32 v[2:3], v[0:1], v[14:15]
	v_pk_add_f32 v[4:5], v[4:5], v[12:13]
	s_nop 0
	v_cvt_pk_bf16_f32 v0, v4, v5
	v_cvt_pk_bf16_f32 v1, v6, v7
	v_cvt_pk_bf16_f32 v2, v2, v3
	v_cvt_pk_bf16_f32 v3, v8, v9
	global_store_dwordx4 v[20:21], v[0:3], off offset:256
	s_cbranch_vccnz .LBB0_1065
	s_andn2_b64 vcc, exec, s[8:9]
	s_cbranch_vccnz .LBB0_1064
	s_barrier
	s_branch .LBB0_1064
